# C2 + staging waves: reciprocals into dead temporaries (chunk decay stays in its register, no copy) and two redundant filler s_nops removed
# speedup vs baseline: 1.0100x; 1.0015x over previous
.Lsc_gf_go1:
	ds_read_b32 v185, v183
	s_waitcnt lgkmcnt(0)
	v_and_b32_e32 v185, v174, v185
	v_fma_f32 v189, v131, s14, v185
	ds_write_b32 v182, v189
	s_waitcnt lgkmcnt(0)
	ds_write_b32 v162, v146
	v_fma_f32 v124, v124, s14, v185
	v_fma_f32 v125, v125, s14, v185
	v_fma_f32 v126, v126, s14, v185
	v_fma_f32 v127, v127, s14, v185
	v_fma_f32 v128, v128, s14, v185
	v_fma_f32 v129, v129, s14, v185
	v_fma_f32 v130, v130, s14, v185
	v_fma_f32 v131, v131, s14, v185
	v_exp_f32_e64 v188, -v185
	v_exp_f32_e64 v124, -v124
	v_exp_f32_e64 v125, -v125
	v_exp_f32_e64 v126, -v126
	v_exp_f32_e64 v127, -v127
	v_exp_f32_e64 v128, -v128
	v_exp_f32_e64 v129, -v129
	v_exp_f32_e64 v130, -v130
	v_exp_f32_e64 v131, -v131
	ds_write_b32 v155, v188
	ds_write_b32 v155, v124 offset:256
	ds_write_b32 v155, v125 offset:512
	ds_write_b32 v155, v126 offset:768
	ds_write_b32 v155, v127 offset:1024
	ds_write_b32 v155, v128 offset:1280
	ds_write_b32 v155, v129 offset:1536
	ds_write_b32 v155, v130 offset:1792
	ds_write_b32 v155, v131 offset:2048
	s_waitcnt lgkmcnt(0)
	ds_read_b128 v[64:67], v153 offset:2048
	ds_read_b128 v[68:71], v153 offset:2176
	ds_read_b128 v[116:119], v153 offset:2304
	ds_read_b128 v[120:123], v153 offset:2432
	s_waitcnt lgkmcnt(0)
	v_rcp_f32_e32 v106, v116
	v_rcp_f32_e32 v107, v117
	v_rcp_f32_e32 v108, v118
	v_rcp_f32_e32 v109, v119
	v_rcp_f32_e32 v110, v120
	v_rcp_f32_e32 v111, v121
	v_rcp_f32_e32 v112, v122
	v_rcp_f32_e32 v113, v123
	v_pk_mul_f32 v[72:73], v[72:73], v[106:107]
	v_pk_mul_f32 v[80:81], v[80:81], v[106:107]
	v_pk_mul_f32 v[88:89], v[88:89], v[64:65]
	v_pk_mul_f32 v[96:97], v[96:97], v[116:117]
	v_pk_mul_f32 v[74:75], v[74:75], v[108:109]
	v_pk_mul_f32 v[82:83], v[82:83], v[108:109]
	v_pk_mul_f32 v[90:91], v[90:91], v[66:67]
	v_pk_mul_f32 v[98:99], v[98:99], v[118:119]
	v_pk_mul_f32 v[76:77], v[76:77], v[110:111]
	v_pk_mul_f32 v[84:85], v[84:85], v[110:111]
	v_pk_mul_f32 v[92:93], v[92:93], v[68:69]
	v_pk_mul_f32 v[100:101], v[100:101], v[120:121]
	v_pk_mul_f32 v[78:79], v[78:79], v[112:113]
	v_pk_mul_f32 v[86:87], v[86:87], v[112:113]
	v_pk_mul_f32 v[94:95], v[94:95], v[70:71]
	v_pk_mul_f32 v[102:103], v[102:103], v[122:123]
	global_load_dwordx2 v[28:29], v5, s[36:37]
	global_load_dwordx2 v[30:31], v5, s[36:37] offset:64
	global_load_dwordx2 v[32:33], v5, s[38:39]
	global_load_dwordx2 v[34:35], v5, s[38:39] offset:64
	global_load_dwordx2 v[36:37], v5, s[40:41]
	global_load_dwordx2 v[38:39], v5, s[40:41] offset:64
	global_load_dwordx2 v[40:41], v5, s[42:43]
	global_load_dwordx2 v[42:43], v5, s[42:43] offset:64
	global_load_dword v44, v6, s[46:47]
	global_load_dword v45, v9, s[44:45]
	v_add_u32_e32 v5, s54, v5
	v_add_u32_e32 v6, s55, v6
	v_add_u32_e32 v9, s54, v9
	ds_write_b32 v159, v131 offset:0
	ds_write_b128 v8, v[72:75] offset:0
	s_sleep 1
	ds_write_b128 v8, v[76:79] offset:128
	ds_write_b128 v8, v[80:83] offset:256
	s_sleep 1
	ds_write_b128 v8, v[84:87] offset:384
	ds_write2_b32 v138, v96, v97 offset0:1 offset1:3
	s_sleep 1
	ds_write2_b32 v139, v88, v89 offset0:0 offset1:2
	ds_write2_b32 v138, v98, v99 offset0:65 offset1:67
	s_sleep 1
	ds_write2_b32 v139, v90, v91 offset0:64 offset1:66
	ds_write2_b32 v138, v100, v101 offset0:33 offset1:35
	s_sleep 1
	ds_write2_b32 v139, v92, v93 offset0:32 offset1:34
	ds_write2_b32 v138, v102, v103 offset0:97 offset1:99
	s_sleep 1
	ds_write2_b32 v139, v94, v95 offset0:96 offset1:98
	ds_write2_b32 v142, v104, v105 offset1:36
	s_sleep 1
	s_cmp_lg_u32 s7, 4
	s_cbranch_scc1 .Lsc_nokb1
	s_and_saveexec_b64 s[68:69], s[12:13]
	ds_write_b128 v158, v[88:91] offset:0
	ds_write_b128 v158, v[92:95] offset:128
	s_mov_b64 exec, s[68:69]

.Lsc_gf_go2:
	ds_read_b32 v185, v183
	s_waitcnt lgkmcnt(0)
	v_and_b32_e32 v185, v174, v185
	v_fma_f32 v189, v131, s14, v185
	ds_write_b32 v182, v189
	s_waitcnt lgkmcnt(0)
	ds_write_b32 v162, v146
	v_fma_f32 v124, v124, s14, v185
	v_fma_f32 v125, v125, s14, v185
	v_fma_f32 v126, v126, s14, v185
	v_fma_f32 v127, v127, s14, v185
	v_fma_f32 v128, v128, s14, v185
	v_fma_f32 v129, v129, s14, v185
	v_fma_f32 v130, v130, s14, v185
	v_fma_f32 v131, v131, s14, v185
	v_exp_f32_e64 v188, -v185
	v_exp_f32_e64 v124, -v124
	v_exp_f32_e64 v125, -v125
	v_exp_f32_e64 v126, -v126
	v_exp_f32_e64 v127, -v127
	v_exp_f32_e64 v128, -v128
	v_exp_f32_e64 v129, -v129
	v_exp_f32_e64 v130, -v130
	v_exp_f32_e64 v131, -v131
	ds_write_b32 v155, v188
	ds_write_b32 v155, v124 offset:256
	ds_write_b32 v155, v125 offset:512
	ds_write_b32 v155, v126 offset:768
	ds_write_b32 v155, v127 offset:1024
	ds_write_b32 v155, v128 offset:1280
	ds_write_b32 v155, v129 offset:1536
	ds_write_b32 v155, v130 offset:1792
	ds_write_b32 v155, v131 offset:2048
	s_waitcnt lgkmcnt(0)
	ds_read_b128 v[64:67], v153 offset:2048
	ds_read_b128 v[68:71], v153 offset:2176
	ds_read_b128 v[116:119], v153 offset:2304
	ds_read_b128 v[120:123], v153 offset:2432
	s_waitcnt lgkmcnt(0)
	v_rcp_f32_e32 v106, v116
	v_rcp_f32_e32 v107, v117
	v_rcp_f32_e32 v108, v118
	v_rcp_f32_e32 v109, v119
	v_rcp_f32_e32 v110, v120
	v_rcp_f32_e32 v111, v121
	v_rcp_f32_e32 v112, v122
	v_rcp_f32_e32 v113, v123
	v_pk_mul_f32 v[72:73], v[72:73], v[106:107]
	v_pk_mul_f32 v[80:81], v[80:81], v[106:107]
	v_pk_mul_f32 v[88:89], v[88:89], v[64:65]
	v_pk_mul_f32 v[96:97], v[96:97], v[116:117]
	v_pk_mul_f32 v[74:75], v[74:75], v[108:109]
	v_pk_mul_f32 v[82:83], v[82:83], v[108:109]
	v_pk_mul_f32 v[90:91], v[90:91], v[66:67]
	v_pk_mul_f32 v[98:99], v[98:99], v[118:119]
	v_pk_mul_f32 v[76:77], v[76:77], v[110:111]
	v_pk_mul_f32 v[84:85], v[84:85], v[110:111]
	v_pk_mul_f32 v[92:93], v[92:93], v[68:69]
	v_pk_mul_f32 v[100:101], v[100:101], v[120:121]
	v_pk_mul_f32 v[78:79], v[78:79], v[112:113]
	v_pk_mul_f32 v[86:87], v[86:87], v[112:113]
	v_pk_mul_f32 v[94:95], v[94:95], v[70:71]
	v_pk_mul_f32 v[102:103], v[102:103], v[122:123]
	global_load_dwordx2 v[46:47], v5, s[36:37]
	global_load_dwordx2 v[48:49], v5, s[36:37] offset:64
	global_load_dwordx2 v[50:51], v5, s[38:39]
	global_load_dwordx2 v[52:53], v5, s[38:39] offset:64
	global_load_dwordx2 v[54:55], v5, s[40:41]
	global_load_dwordx2 v[56:57], v5, s[40:41] offset:64
	global_load_dwordx2 v[58:59], v5, s[42:43]
	global_load_dwordx2 v[60:61], v5, s[42:43] offset:64
	global_load_dword v62, v6, s[46:47]
	global_load_dword v63, v9, s[44:45]
	v_add_u32_e32 v5, s54, v5
	v_add_u32_e32 v6, s55, v6
	v_add_u32_e32 v9, s54, v9
	ds_write_b32 v159, v131 offset:34816
	ds_write_b128 v8, v[72:75] offset:34816
	s_sleep 1
	ds_write_b128 v8, v[76:79] offset:34944
	ds_write_b128 v8, v[80:83] offset:35072
	s_sleep 1
	ds_write_b128 v8, v[84:87] offset:35200
	ds_write2_b32 v140, v96, v97 offset0:1 offset1:3
	s_sleep 1
	ds_write2_b32 v141, v88, v89 offset0:0 offset1:2
	ds_write2_b32 v140, v98, v99 offset0:65 offset1:67
	s_sleep 1
	ds_write2_b32 v141, v90, v91 offset0:64 offset1:66
	ds_write2_b32 v140, v100, v101 offset0:33 offset1:35
	s_sleep 1
	ds_write2_b32 v141, v92, v93 offset0:32 offset1:34
	ds_write2_b32 v140, v102, v103 offset0:97 offset1:99
	s_sleep 1
	ds_write2_b32 v141, v94, v95 offset0:96 offset1:98
	ds_write2_b32 v143, v104, v105 offset1:36
	s_sleep 1
	s_cmp_lg_u32 s7, 4
	s_cbranch_scc1 .Lsc_nokb2
	s_and_saveexec_b64 s[68:69], s[12:13]
	ds_write_b128 v158, v[88:91] offset:34816
	ds_write_b128 v158, v[92:95] offset:34944
	s_mov_b64 exec, s[68:69]

.Lsc_gf_go3:
	ds_read_b32 v185, v183
	s_waitcnt lgkmcnt(0)
	v_and_b32_e32 v185, v174, v185
	v_fma_f32 v189, v131, s14, v185
	ds_write_b32 v182, v189
	s_waitcnt lgkmcnt(0)
	ds_write_b32 v162, v146
	v_fma_f32 v124, v124, s14, v185
	v_fma_f32 v125, v125, s14, v185
	v_fma_f32 v126, v126, s14, v185
	v_fma_f32 v127, v127, s14, v185
	v_fma_f32 v128, v128, s14, v185
	v_fma_f32 v129, v129, s14, v185
	v_fma_f32 v130, v130, s14, v185
	v_fma_f32 v131, v131, s14, v185
	v_exp_f32_e64 v188, -v185
	v_exp_f32_e64 v124, -v124
	v_exp_f32_e64 v125, -v125
	v_exp_f32_e64 v126, -v126
	v_exp_f32_e64 v127, -v127
	v_exp_f32_e64 v128, -v128
	v_exp_f32_e64 v129, -v129
	v_exp_f32_e64 v130, -v130
	v_exp_f32_e64 v131, -v131
	ds_write_b32 v155, v188
	ds_write_b32 v155, v124 offset:256
	ds_write_b32 v155, v125 offset:512
	ds_write_b32 v155, v126 offset:768
	ds_write_b32 v155, v127 offset:1024
	ds_write_b32 v155, v128 offset:1280
	ds_write_b32 v155, v129 offset:1536
	ds_write_b32 v155, v130 offset:1792
	ds_write_b32 v155, v131 offset:2048
	s_waitcnt lgkmcnt(0)
	ds_read_b128 v[64:67], v153 offset:2048
	ds_read_b128 v[68:71], v153 offset:2176
	ds_read_b128 v[116:119], v153 offset:2304
	ds_read_b128 v[120:123], v153 offset:2432
	s_waitcnt lgkmcnt(0)
	v_rcp_f32_e32 v106, v116
	v_rcp_f32_e32 v107, v117
	v_rcp_f32_e32 v108, v118
	v_rcp_f32_e32 v109, v119
	v_rcp_f32_e32 v110, v120
	v_rcp_f32_e32 v111, v121
	v_rcp_f32_e32 v112, v122
	v_rcp_f32_e32 v113, v123
	v_pk_mul_f32 v[72:73], v[72:73], v[106:107]
	v_pk_mul_f32 v[80:81], v[80:81], v[106:107]
	v_pk_mul_f32 v[88:89], v[88:89], v[64:65]
	v_pk_mul_f32 v[96:97], v[96:97], v[116:117]
	v_pk_mul_f32 v[74:75], v[74:75], v[108:109]
	v_pk_mul_f32 v[82:83], v[82:83], v[108:109]
	v_pk_mul_f32 v[90:91], v[90:91], v[66:67]
	v_pk_mul_f32 v[98:99], v[98:99], v[118:119]
	v_pk_mul_f32 v[76:77], v[76:77], v[110:111]
	v_pk_mul_f32 v[84:85], v[84:85], v[110:111]
	v_pk_mul_f32 v[92:93], v[92:93], v[68:69]
	v_pk_mul_f32 v[100:101], v[100:101], v[120:121]
	v_pk_mul_f32 v[78:79], v[78:79], v[112:113]
	v_pk_mul_f32 v[86:87], v[86:87], v[112:113]
	v_pk_mul_f32 v[94:95], v[94:95], v[70:71]
	v_pk_mul_f32 v[102:103], v[102:103], v[122:123]
	global_load_dwordx2 v[28:29], v5, s[36:37]
	global_load_dwordx2 v[30:31], v5, s[36:37] offset:64
	global_load_dwordx2 v[32:33], v5, s[38:39]
	global_load_dwordx2 v[34:35], v5, s[38:39] offset:64
	global_load_dwordx2 v[36:37], v5, s[40:41]
	global_load_dwordx2 v[38:39], v5, s[40:41] offset:64
	global_load_dwordx2 v[40:41], v5, s[42:43]
	global_load_dwordx2 v[42:43], v5, s[42:43] offset:64
	global_load_dword v44, v6, s[46:47]
	global_load_dword v45, v9, s[44:45]
	v_add_u32_e32 v5, s54, v5
	v_add_u32_e32 v6, s55, v6
	v_add_u32_e32 v9, s54, v9
	s_sub_u32 s65, s6, 1
	ds_read_b128 v[148:151], v144
	s_waitcnt lgkmcnt(0)
	v_min_u32_e32 v148, v148, v149
	v_min3_u32 v148, v148, v150, v151
	s_nop 1
	v_readfirstlane_b32 s68, v148
	s_cmp_ge_u32 s68, s65
	s_cbranch_scc1 .Lsc_G_gom0
	s_mov_b32 s69, 0x100000

.Lsc_G_gom0:
	ds_write_b32 v159, v131 offset:0
	ds_write_b128 v8, v[72:75] offset:0
	s_sleep 1
	ds_write_b128 v8, v[76:79] offset:128
	ds_write_b128 v8, v[80:83] offset:256
	s_sleep 1
	ds_write_b128 v8, v[84:87] offset:384
	ds_write2_b32 v138, v96, v97 offset0:1 offset1:3
	s_sleep 1
	ds_write2_b32 v139, v88, v89 offset0:0 offset1:2
	ds_write2_b32 v138, v98, v99 offset0:65 offset1:67
	s_sleep 1
	ds_write2_b32 v139, v90, v91 offset0:64 offset1:66
	ds_write2_b32 v138, v100, v101 offset0:33 offset1:35
	s_sleep 1
	ds_write2_b32 v139, v92, v93 offset0:32 offset1:34
	ds_write2_b32 v138, v102, v103 offset0:97 offset1:99
	s_sleep 1
	ds_write2_b32 v139, v94, v95 offset0:96 offset1:98
	ds_write2_b32 v142, v104, v105 offset1:36
	s_sleep 1
	s_cmp_lg_u32 s7, 4
	s_cbranch_scc1 .Lsc_nokb3
	s_and_saveexec_b64 s[68:69], s[12:13]
	ds_write_b128 v158, v[88:91] offset:0
	ds_write_b128 v158, v[92:95] offset:128
	s_mov_b64 exec, s[68:69]

.Lsc_gf_go4:
	ds_read_b32 v185, v183
	s_waitcnt lgkmcnt(0)
	v_and_b32_e32 v185, v174, v185
	v_fma_f32 v189, v131, s14, v185
	ds_write_b32 v182, v189
	s_waitcnt lgkmcnt(0)
	ds_write_b32 v162, v146
	v_fma_f32 v124, v124, s14, v185
	v_fma_f32 v125, v125, s14, v185
	v_fma_f32 v126, v126, s14, v185
	v_fma_f32 v127, v127, s14, v185
	v_fma_f32 v128, v128, s14, v185
	v_fma_f32 v129, v129, s14, v185
	v_fma_f32 v130, v130, s14, v185
	v_fma_f32 v131, v131, s14, v185
	v_exp_f32_e64 v188, -v185
	v_exp_f32_e64 v124, -v124
	v_exp_f32_e64 v125, -v125
	v_exp_f32_e64 v126, -v126
	v_exp_f32_e64 v127, -v127
	v_exp_f32_e64 v128, -v128
	v_exp_f32_e64 v129, -v129
	v_exp_f32_e64 v130, -v130
	v_exp_f32_e64 v131, -v131
	ds_write_b32 v155, v188
	ds_write_b32 v155, v124 offset:256
	ds_write_b32 v155, v125 offset:512
	ds_write_b32 v155, v126 offset:768
	ds_write_b32 v155, v127 offset:1024
	ds_write_b32 v155, v128 offset:1280
	ds_write_b32 v155, v129 offset:1536
	ds_write_b32 v155, v130 offset:1792
	ds_write_b32 v155, v131 offset:2048
	s_waitcnt lgkmcnt(0)
	ds_read_b128 v[64:67], v153 offset:2048
	ds_read_b128 v[68:71], v153 offset:2176
	ds_read_b128 v[116:119], v153 offset:2304
	ds_read_b128 v[120:123], v153 offset:2432
	s_waitcnt lgkmcnt(0)
	v_rcp_f32_e32 v106, v116
	v_rcp_f32_e32 v107, v117
	v_rcp_f32_e32 v108, v118
	v_rcp_f32_e32 v109, v119
	v_rcp_f32_e32 v110, v120
	v_rcp_f32_e32 v111, v121
	v_rcp_f32_e32 v112, v122
	v_rcp_f32_e32 v113, v123
	v_pk_mul_f32 v[72:73], v[72:73], v[106:107]
	v_pk_mul_f32 v[80:81], v[80:81], v[106:107]
	v_pk_mul_f32 v[88:89], v[88:89], v[64:65]
	v_pk_mul_f32 v[96:97], v[96:97], v[116:117]
	v_pk_mul_f32 v[74:75], v[74:75], v[108:109]
	v_pk_mul_f32 v[82:83], v[82:83], v[108:109]
	v_pk_mul_f32 v[90:91], v[90:91], v[66:67]
	v_pk_mul_f32 v[98:99], v[98:99], v[118:119]
	v_pk_mul_f32 v[76:77], v[76:77], v[110:111]
	v_pk_mul_f32 v[84:85], v[84:85], v[110:111]
	v_pk_mul_f32 v[92:93], v[92:93], v[68:69]
	v_pk_mul_f32 v[100:101], v[100:101], v[120:121]
	v_pk_mul_f32 v[78:79], v[78:79], v[112:113]
	v_pk_mul_f32 v[86:87], v[86:87], v[112:113]
	v_pk_mul_f32 v[94:95], v[94:95], v[70:71]
	v_pk_mul_f32 v[102:103], v[102:103], v[122:123]
	global_load_dwordx2 v[46:47], v5, s[36:37]
	global_load_dwordx2 v[48:49], v5, s[36:37] offset:64
	global_load_dwordx2 v[50:51], v5, s[38:39]
	global_load_dwordx2 v[52:53], v5, s[38:39] offset:64
	global_load_dwordx2 v[54:55], v5, s[40:41]
	global_load_dwordx2 v[56:57], v5, s[40:41] offset:64
	global_load_dwordx2 v[58:59], v5, s[42:43]
	global_load_dwordx2 v[60:61], v5, s[42:43] offset:64
	global_load_dword v62, v6, s[46:47]
	global_load_dword v63, v9, s[44:45]
	v_add_u32_e32 v5, s54, v5
	v_add_u32_e32 v6, s55, v6
	v_add_u32_e32 v9, s54, v9
	s_sub_u32 s65, s6, 1
	ds_read_b128 v[148:151], v144
	s_waitcnt lgkmcnt(0)
	v_min_u32_e32 v148, v148, v149
	v_min3_u32 v148, v148, v150, v151
	s_nop 1
	v_readfirstlane_b32 s68, v148
	s_cmp_ge_u32 s68, s65
	s_cbranch_scc1 .Lsc_G_gom1
	s_mov_b32 s69, 0x100000

.Lsc_G_gom1:
	ds_write_b32 v159, v131 offset:34816
	ds_write_b128 v8, v[72:75] offset:34816
	s_sleep 1
	ds_write_b128 v8, v[76:79] offset:34944
	ds_write_b128 v8, v[80:83] offset:35072
	s_sleep 1
	ds_write_b128 v8, v[84:87] offset:35200
	ds_write2_b32 v140, v96, v97 offset0:1 offset1:3
	s_sleep 1
	ds_write2_b32 v141, v88, v89 offset0:0 offset1:2
	ds_write2_b32 v140, v98, v99 offset0:65 offset1:67
	s_sleep 1
	ds_write2_b32 v141, v90, v91 offset0:64 offset1:66
	ds_write2_b32 v140, v100, v101 offset0:33 offset1:35
	s_sleep 1
	ds_write2_b32 v141, v92, v93 offset0:32 offset1:34
	ds_write2_b32 v140, v102, v103 offset0:97 offset1:99
	s_sleep 1
	ds_write2_b32 v141, v94, v95 offset0:96 offset1:98
	ds_write2_b32 v143, v104, v105 offset1:36
	s_sleep 1
	s_cmp_lg_u32 s7, 4
	s_cbranch_scc1 .Lsc_nokb4
	s_and_saveexec_b64 s[68:69], s[12:13]
	ds_write_b128 v158, v[88:91] offset:34816
	ds_write_b128 v158, v[92:95] offset:34944
	s_mov_b64 exec, s[68:69]

.Lsc_gf_go5:
	ds_read_b32 v185, v183
	s_waitcnt lgkmcnt(0)
	v_and_b32_e32 v185, v174, v185
	v_fma_f32 v189, v131, s14, v185
	ds_write_b32 v182, v189
	s_waitcnt lgkmcnt(0)
	ds_write_b32 v162, v146
	v_fma_f32 v124, v124, s14, v185
	v_fma_f32 v125, v125, s14, v185
	v_fma_f32 v126, v126, s14, v185
	v_fma_f32 v127, v127, s14, v185
	v_fma_f32 v128, v128, s14, v185
	v_fma_f32 v129, v129, s14, v185
	v_fma_f32 v130, v130, s14, v185
	v_fma_f32 v131, v131, s14, v185
	v_exp_f32_e64 v188, -v185
	v_exp_f32_e64 v124, -v124
	v_exp_f32_e64 v125, -v125
	v_exp_f32_e64 v126, -v126
	v_exp_f32_e64 v127, -v127
	v_exp_f32_e64 v128, -v128
	v_exp_f32_e64 v129, -v129
	v_exp_f32_e64 v130, -v130
	v_exp_f32_e64 v131, -v131
	ds_write_b32 v155, v188
	ds_write_b32 v155, v124 offset:256
	ds_write_b32 v155, v125 offset:512
	ds_write_b32 v155, v126 offset:768
	ds_write_b32 v155, v127 offset:1024
	ds_write_b32 v155, v128 offset:1280
	ds_write_b32 v155, v129 offset:1536
	ds_write_b32 v155, v130 offset:1792
	ds_write_b32 v155, v131 offset:2048
	s_waitcnt lgkmcnt(0)
	ds_read_b128 v[64:67], v153 offset:2048
	ds_read_b128 v[68:71], v153 offset:2176
	ds_read_b128 v[116:119], v153 offset:2304
	ds_read_b128 v[120:123], v153 offset:2432
	s_waitcnt lgkmcnt(0)
	v_rcp_f32_e32 v106, v116
	v_rcp_f32_e32 v107, v117
	v_rcp_f32_e32 v108, v118
	v_rcp_f32_e32 v109, v119
	v_rcp_f32_e32 v110, v120
	v_rcp_f32_e32 v111, v121
	v_rcp_f32_e32 v112, v122
	v_rcp_f32_e32 v113, v123
	v_pk_mul_f32 v[72:73], v[72:73], v[106:107]
	v_pk_mul_f32 v[80:81], v[80:81], v[106:107]
	v_pk_mul_f32 v[88:89], v[88:89], v[64:65]
	v_pk_mul_f32 v[96:97], v[96:97], v[116:117]
	v_pk_mul_f32 v[74:75], v[74:75], v[108:109]
	v_pk_mul_f32 v[82:83], v[82:83], v[108:109]
	v_pk_mul_f32 v[90:91], v[90:91], v[66:67]
	v_pk_mul_f32 v[98:99], v[98:99], v[118:119]
	v_pk_mul_f32 v[76:77], v[76:77], v[110:111]
	v_pk_mul_f32 v[84:85], v[84:85], v[110:111]
	v_pk_mul_f32 v[92:93], v[92:93], v[68:69]
	v_pk_mul_f32 v[100:101], v[100:101], v[120:121]
	v_pk_mul_f32 v[78:79], v[78:79], v[112:113]
	v_pk_mul_f32 v[86:87], v[86:87], v[112:113]
	v_pk_mul_f32 v[94:95], v[94:95], v[70:71]
	v_pk_mul_f32 v[102:103], v[102:103], v[122:123]
	s_sub_u32 s65, s6, 1
	ds_read_b128 v[148:151], v144
	s_waitcnt lgkmcnt(0)
	v_min_u32_e32 v148, v148, v149
	v_min3_u32 v148, v148, v150, v151
	s_nop 1
	v_readfirstlane_b32 s68, v148
	s_cmp_ge_u32 s68, s65
	s_cbranch_scc1 .Lsc_G_goz0
	s_mov_b32 s69, 0x100000
